# attention unit prologue: tile-1 K/V loads issued right after the first barrier so they overlap the first QK^T
# speedup vs baseline: 1.0004x; 1.0004x over previous
; __device__ __forceinline__ int tid_of(int wv) { int l; asm volatile("v_mbcnt_lo_u32_b32 %0, -1, 0\n\tv_mbcnt_hi_u32_b32 %0, -1, %0" : "=v"(l)); return wv * 64 + l; }
; __device__ __forceinline__ void attn_dense_body(const bf16* __restrict__ Qb, const bf16* __restrict__ Kn, const bf16* __restrict__ Kr, const bf16* __restrict__ Vh,
;                                                 bf16* __restrict__ Ob, pg8::u64* ssa, int seq, char* lds, const int wv) {
;   const int tid = tid_of(wv), wid = tid >> 6, lane = tid & 63, r32 = lane & 31, hi = lane >> 5;
;   char* V_lds = lds + OFF_V; char* K_lds = lds + OFF_K; char* KR_lds = lds + OFF_KR;
;   float* ws = (float*)(lds + OFF_WS) + wid * 64; float* li_l = ws; float* al_l = ws + 32;
;   float m_reg = -1e30f, l_reg = 0; f32x16 o[4] = {}; bf16x8 qr[NQR]; char* ql = lds + OFF_QL + wid * (NQL * 1024) + lane * 16;
;   const bf16* Qw = Qb + (long)(wid * QBLK + r32) * LDQ + hi * 8;
; #pragma unroll
;   for (int d0 = 0; d0 < 12; ++d0) { const bf16x8 t = *reinterpret_cast<const bf16x8*>(Qw + d0 * 16); if (d0 < NQR) qr[d0 < NQR ? d0 : 0] = t; else *reinterpret_cast<bf16x8*>(ql + (d0 - NQR) * 1024) = t; }
;   const int sr = tid >> 4, sc = (tid & 15) * 8, vst0 = v_st(sr, sc), vst1 = v_st(32 + sr, sc);
;   const int krr = tid >> 3, krc = (tid & 7) * 8;
;   const int vb0 = (int)(uintptr_t)V_lds + v_rd_base(lane);
;   struct { bf16x8 vs0, vs1, ks0, ks1, kr; } sr_[SDEPTH];
; const unsigned offV0 = (unsigned)(sr * LDKV + sc) * 2u, offV1 = (unsigned)((32 + sr) * LDKV + sc) * 2u, offKR = (unsigned)(krr * LDKR + krc) * 2u;
;     ...
;   f32x16 pA0, pA1, pB0, pB1; float mnA, mnB, alA, alB; bf16x8 pa0, pa1, pa2, pa3; const int NT = seq / KVBLK;
;   constexpr int SE = 0, SO = SDEPTH - 1;
;   SLOAD(SE, 0); asm volatile("s_waitcnt vmcnt(0)" ::: "memory"); SWRITE(0, SE); __syncthreads();
;   qkt(pA0, pA1, K_lds, KR_lds, qr, ql, r32, hi); partialSM(pA0, pA1, m_reg, mnA, alA);
;   SLOAD(SO, KVBLK); if constexpr (SDEPTH == 2) { if (2 < NT) SLOAD(SE, 2 * KVBLK); }
; __global__ void __launch_bounds__(512) mk_fwd(Args args) {
;     ...
;             __syncthreads();
;             att::attn_dense_body(Q + (size_t)row0 * QW + head * 192, KV + (size_t)krow0 * KVW + head * 256, Z + (size_t)krow0 * ZW + Z_KR, KV + (size_t)krow0 * KVW + head * 256 + 128,
;                                  H + (size_t)row0 * DM + head * 128, SSA + row0, seq, (char*)lds_raw, wv);
.LBB0_1151:
	s_and_b32 s2, s78, 7
	s_lshl_b32 s82, s2, 9
	s_lshl_b32 s2, s79, 5
	s_and_b32 s3, s2, 0x7ffff800
	s_cmpk_lt_i32 s79, 0x100
	s_cselect_b32 s20, 0, s3
	s_cselect_b32 s3, s53, 0x7fffff00
	s_cselect_b32 s81, 0x80, 32
	s_and_b32 s58, s2, s3
	s_and_b32 s80, s79, 7
	s_ashr_i32 s59, s58, 31
	s_mul_i32 s3, s58, 0xc00
	s_mul_hi_i32 s2, s58, 0xc00
	s_add_u32 s3, s6, s3
	s_addc_u32 s2, s7, s2
	s_mul_i32 s4, s80, 0x180
	s_add_u32 s62, s3, s4
	s_barrier
	s_addc_u32 s63, s2, 0
	s_lshl_b64 s[4:5], s[20:21], 12
	v_mbcnt_lo_u32_b32 v49, -1, 0
	v_mbcnt_hi_u32_b32 v49, -1, v49
	s_add_u32 s2, s22, s4
	v_add_u32_e32 v51, s33, v49
	v_lshlrev_b32_e32 v23, 3, v51
	s_addc_u32 s3, s23, s5
	s_lshl_b32 s60, s80, 9
	v_and_b32_e32 v0, 0x78, v23
	s_add_u32 s2, s2, s60
	v_ashrrev_i32_e32 v22, 4, v51
	v_lshlrev_b32_e32 v24, 1, v0
	s_addc_u32 s3, s3, 0
	v_lshl_or_b32 v48, v22, 12, v24
	s_waitcnt lgkmcnt(0)
	global_load_dwordx4 v[0:3], v48, s[2:3] offset:256
	global_load_dwordx4 v[8:11], v48, s[2:3]
	v_ashrrev_i32_e32 v26, 3, v51
	v_add_u32_e32 v25, 32, v22
	s_mul_i32 s60, s20, 0x1a00
	v_and_b32_e32 v27, 56, v23
	v_mul_lo_u32 v16, v26, s67
	v_lshl_or_b32 v50, v25, 12, v24
	s_mul_hi_u32 s61, s20, 0x1a00
	s_add_u32 s60, s14, s60
	v_or_b32_e32 v16, v16, v27
	global_load_dwordx4 v[4:7], v50, s[2:3] offset:256
	global_load_dwordx4 v[12:15], v50, s[2:3]
	s_addc_u32 s61, s15, s61
	v_lshlrev_b32_e32 v52, 1, v16
	global_load_dwordx4 v[16:19], v52, s[60:61] offset:2048
	v_ashrrev_i32_e32 v74, 1, v51
	v_bfe_u32 v192, v49, 5, 1
	v_bfi_b32 v28, s66, v74, v49
	v_mov_b64_e32 v[20:21], s[62:63]
	v_mad_i64_i32 v[20:21], s[62:63], v28, s64, v[20:21]
	v_lshlrev_b32_e32 v168, 4, v192
	v_lshl_add_u64 v[20:21], v[20:21], 0, v[168:169]
	global_load_dwordx4 v[124:127], v[20:21], off
	global_load_dwordx4 v[128:131], v[20:21], off offset:32
	global_load_dwordx4 v[140:143], v[20:21], off offset:64
	global_load_dwordx4 v[136:139], v[20:21], off offset:96
	global_load_dwordx4 v[132:135], v[20:21], off offset:128
	global_load_dwordx4 v[120:123], v[20:21], off offset:160
	global_load_dwordx4 v[116:119], v[20:21], off offset:192
	global_load_dwordx4 v[112:115], v[20:21], off offset:224
	global_load_dwordx4 v[108:111], v[20:21], off offset:256
	global_load_dwordx4 v[104:107], v[20:21], off offset:288
	global_load_dwordx4 v[100:103], v[20:21], off offset:320
	global_load_dwordx4 v[96:99], v[20:21], off offset:352
	v_and_b32_e32 v28, 0xfffff0, v22
	v_lshlrev_b32_e32 v29, 1, v22
	v_and_or_b32 v28, v29, 8, v28
	v_lshrrev_b32_e32 v30, 1, v22
	v_bfe_u32 v23, v23, 5, 2
	v_and_b32_e32 v31, 3, v22
	v_lshrrev_b32_e32 v28, 1, v28
	v_and_or_b32 v29, v30, 4, v31
	v_or_b32_e32 v28, v28, v23
	v_lshlrev_b32_e32 v29, 6, v29
	v_and_b32_e32 v32, 48, v24
	v_lshlrev_b32_e32 v28, 9, v28
	v_or3_b32 v28, v28, v29, v32
	v_and_b32_e32 v30, 0xfffff0, v25
	v_lshlrev_b32_e32 v31, 1, v25
	v_add_u32_e32 v198, 0, v28
	v_and_or_b32 v30, v31, 8, v30
	s_waitcnt vmcnt(0)
	v_lshrrev_b32_e32 v30, 1, v30
	v_or_b32_e32 v23, v30, v23
	v_lshlrev_b32_e32 v23, 9, v23
	v_or3_b32 v23, v23, v29, v32
	v_and_b32_e32 v193, 31, v49
	v_lshlrev_b32_e32 v75, 4, v49
	v_add_u32_e32 v199, 0, v23
	s_cmp_lg_u32 0, -1
	v_mov_b32_e32 v53, v169
	s_cselect_b32 s62, 0, 0
	v_and_b32_e32 v170, 0xffffffe0, v74
	v_and_b32_e32 v79, 63, v49
	v_mov_b32_e32 v195, 0
	s_waitcnt vmcnt(16)
	ds_write_b128 v198, v[0:3]
	v_lshlrev_b32_e32 v0, 8, v22
	v_and_b32_e32 v1, 0xf0, v51
	v_bitop3_b32 v0, v24, v0, v1 bitop3:0xde
	v_add_u32_e32 v200, 0, v0
	v_lshlrev_b32_e32 v0, 8, v25
	v_bitop3_b32 v0, v24, v0, v1 bitop3:0xde
	v_add_u32_e32 v201, 0, v0
	v_lshlrev_b32_e32 v0, 7, v26
	v_lshlrev_b32_e32 v2, 1, v27
	v_and_b32_e32 v1, 0x70, v51
	v_bitop3_b32 v78, v2, v0, v1 bitop3:0xde
	s_waitcnt vmcnt(14)
	ds_write_b128 v199, v[4:7]
	ds_write_b128 v200, v[8:11] offset:32768
	v_add_u32_e32 v0, s68, v78
	v_lshlrev_b32_e32 v8, 8, v193
	v_and_b32_e32 v9, 0xf0, v75
	s_waitcnt vmcnt(13)
	ds_write_b128 v201, v[12:15] offset:32768
	s_waitcnt vmcnt(12)
	ds_write_b128 v0, v[16:19]
	v_bitop3_b32 v0, v168, v8, v9 bitop3:0xde
	v_add_u32_e32 v202, 0, v0
	s_waitcnt lgkmcnt(0)
	s_barrier
	s_add_u32 s98, s2, 0x40100
	s_addc_u32 s99, s3, 0
	s_add_u32 s100, s2, 0x40000
	s_addc_u32 s101, s3, 0
	global_load_dwordx4 v[54:57], v50, s[98:99]
	global_load_dwordx4 v[58:61], v48, s[100:101]
	global_load_dwordx4 v[62:65], v48, s[98:99]
	global_load_dwordx4 v[66:69], v50, s[100:101]
	v_lshl_add_u64 v[70:71], s[60:61], 0, v[52:53]
	s_mov_b32 s98, s70
	s_mov_b32 s99, 0
	v_lshl_add_u64 v[70:71], v[70:71], 0, s[98:99]
	global_load_dwordx4 v[70:73], v[70:71], off offset:2048
	ds_read_b128 v[0:3], v202 offset:32768
	ds_read_b128 v[4:7], v202 offset:40960
	s_waitcnt vmcnt(11) lgkmcnt(1)
	v_mfma_f32_32x32x16_bf16 v[16:31], v[0:3], v[124:127], 0
	v_or_b32_e32 v10, 32, v168
	v_bitop3_b32 v0, v10, v8, v9 bitop3:0xde
	v_add_u32_e32 v203, 0, v0
	v_or_b32_e32 v11, 64, v168
	v_or_b32_e32 v12, 0x60, v168
	v_lshlrev_b32_e32 v13, 7, v193
	v_add_u32_e32 v218, 0, v78
	s_waitcnt lgkmcnt(0)
	v_mfma_f32_32x32x16_bf16 v[32:47], v[4:7], v[124:127], 0
	ds_read_b128 v[0:3], v203 offset:32768
	ds_read_b128 v[4:7], v203 offset:40960
	v_add_u32_e32 v219, 0x12000, v218
	s_waitcnt vmcnt(10) lgkmcnt(1)
	v_mfma_f32_32x32x16_bf16 v[16:31], v[0:3], v[128:131], v[16:31]
	v_bitop3_b32 v0, v11, v8, v9 bitop3:0xde
	v_add_u32_e32 v204, 0, v0
	s_waitcnt lgkmcnt(0)
	v_mfma_f32_32x32x16_bf16 v[32:47], v[4:7], v[128:131], v[32:47]
	ds_read_b128 v[0:3], v204 offset:32768
	ds_read_b128 v[4:7], v204 offset:40960
	s_waitcnt vmcnt(9) lgkmcnt(1)
	v_mfma_f32_32x32x16_bf16 v[16:31], v[0:3], v[140:143], v[16:31]
	v_bitop3_b32 v0, v12, v8, v9 bitop3:0xde
	v_add_u32_e32 v205, 0, v0
	s_waitcnt lgkmcnt(0)
; #define SWAIT() do { if constexpr (SDEPTH == 2) asm volatile("s_waitcnt vmcnt(5)" ::: "memory"); else asm volatile("s_waitcnt vmcnt(0)" ::: "memory"); } while (0)
; __device__ __forceinline__ void qkt(f32x16& p0, f32x16& p1, const char* Ks, const char* Krs, const bf16x8* qr, const char* ql, int r32, int hi) {
;   p0 = f32x16{}; p1 = f32x16{};
; #pragma unroll
;   for (int d0 = 0; d0 < 8; ++d0) { int cb = (d0 * 16 + hi * 8) * 2;
;     bf16x8 b0 = *reinterpret_cast<const bf16x8*>(Ks + KSWZ(r32, cb));
;     bf16x8 b1 = *reinterpret_cast<const bf16x8*>(Ks + KSWZ(32 + r32, cb));
;     const bf16x8 qf = QF(d0);
;     p0 = __builtin_amdgcn_mfma_f32_32x32x16_bf16(b0, qf, p0, 0, 0, 0);
;     p1 = __builtin_amdgcn_mfma_f32_32x32x16_bf16(b1, qf, p1, 0, 0, 0); }
; #pragma unroll
;   for (int d0 = 0; d0 < 4; ++d0) { int cb = (d0 * 16 + hi * 8) * 2;
;     bf16x8 b0 = *reinterpret_cast<const bf16x8*>(Krs + KRSWZ(r32, cb));
;     bf16x8 b1 = *reinterpret_cast<const bf16x8*>(Krs + KRSWZ(32 + r32, cb));
;     const bf16x8 qf = QF(8 + d0);
;     p0 = __builtin_amdgcn_mfma_f32_32x32x16_bf16(b0, qf, p0, 0, 0, 0);
;     p1 = __builtin_amdgcn_mfma_f32_32x32x16_bf16(b1, qf, p1, 0, 0, 0); }
; }
; __device__ __forceinline__ void attn_dense_body(const bf16* __restrict__ Qb, const bf16* __restrict__ Kn, const bf16* __restrict__ Kr, const bf16* __restrict__ Vh,
;                                                 bf16* __restrict__ Ob, pg8::u64* ssa, int seq, char* lds, const int wv) {
;     ...
;   SLOAD(SO, KVBLK); if constexpr (SDEPTH == 2) { if (2 < NT) SLOAD(SE, 2 * KVBLK); }
;   SWAIT(); SWRITE(1, SO); __syncthreads();
	v_mfma_f32_32x32x16_bf16 v[32:47], v[4:7], v[140:143], v[32:47]
	ds_read_b128 v[0:3], v205 offset:32768
	ds_read_b128 v[4:7], v205 offset:40960
	s_waitcnt vmcnt(8) lgkmcnt(1)
	v_mfma_f32_32x32x16_bf16 v[16:31], v[0:3], v[136:139], v[16:31]
	v_or_b32_e32 v0, 0x80, v168
	v_bitop3_b32 v0, v0, v8, v9 bitop3:0xde
	v_add_u32_e32 v206, 0, v0
	s_waitcnt lgkmcnt(0)
	v_mfma_f32_32x32x16_bf16 v[32:47], v[4:7], v[136:139], v[32:47]
	ds_read_b128 v[0:3], v206 offset:32768
	ds_read_b128 v[4:7], v206 offset:40960
	s_waitcnt vmcnt(7) lgkmcnt(1)
	v_mfma_f32_32x32x16_bf16 v[16:31], v[0:3], v[132:135], v[16:31]
	v_or_b32_e32 v0, 0xa0, v168
	v_bitop3_b32 v0, v0, v8, v9 bitop3:0xde
	v_add_u32_e32 v207, 0, v0
	s_waitcnt lgkmcnt(0)
	v_mfma_f32_32x32x16_bf16 v[32:47], v[4:7], v[132:135], v[32:47]
	ds_read_b128 v[0:3], v207 offset:32768
	ds_read_b128 v[4:7], v207 offset:40960
	s_waitcnt vmcnt(6) lgkmcnt(1)
	v_mfma_f32_32x32x16_bf16 v[16:31], v[0:3], v[120:123], v[16:31]
	v_or_b32_e32 v0, 0xc0, v168
	v_bitop3_b32 v0, v0, v8, v9 bitop3:0xde
	v_add_u32_e32 v208, 0, v0
	s_waitcnt lgkmcnt(0)
	v_mfma_f32_32x32x16_bf16 v[32:47], v[4:7], v[120:123], v[32:47]
	ds_read_b128 v[0:3], v208 offset:32768
	ds_read_b128 v[4:7], v208 offset:40960
	s_waitcnt vmcnt(5) lgkmcnt(1)
	v_mfma_f32_32x32x16_bf16 v[16:31], v[0:3], v[116:119], v[16:31]
	v_or_b32_e32 v0, 0xe0, v168
	v_bitop3_b32 v0, v0, v8, v9 bitop3:0xde
	v_add_u32_e32 v209, 0, v0
	v_lshl_add_u64 v[8:9], s[60:61], 0, v[52:53]
	s_add_u32 s60, s2, 0x40100
	s_addc_u32 s61, s3, 0
	s_add_u32 s2, s2, 0x40000
	s_waitcnt lgkmcnt(0)
	v_mfma_f32_32x32x16_bf16 v[32:47], v[4:7], v[116:119], v[32:47]
	ds_read_b128 v[0:3], v209 offset:32768
	ds_read_b128 v[4:7], v209 offset:40960
	s_addc_u32 s3, s3, 0
	s_waitcnt lgkmcnt(1)
	v_mfma_f32_32x32x16_bf16 v[16:31], v[0:3], v[112:115], v[16:31]
	v_lshlrev_b32_e32 v0, 3, v49
	v_and_b32_e32 v14, 0x70, v0
	v_bitop3_b32 v210, v168, v13, v14 bitop3:0xde
	v_add_u32_e32 v211, s68, v210
	v_bitop3_b32 v212, v10, v13, v14 bitop3:0xde
	v_add_u32_e32 v213, s68, v212
	v_bitop3_b32 v214, v11, v13, v14 bitop3:0xde
	s_waitcnt lgkmcnt(0)
	v_mfma_f32_32x32x16_bf16 v[32:47], v[4:7], v[112:115], v[32:47]
	ds_read_b128 v[0:3], v211
	ds_read_b128 v[4:7], v211 offset:4096
	v_add_u32_e32 v215, s68, v214
	v_bitop3_b32 v216, v12, v13, v14 bitop3:0xde
	v_add_u32_e32 v217, s68, v216
	s_waitcnt lgkmcnt(1)
	v_mfma_f32_32x32x16_bf16 v[16:31], v[0:3], v[108:111], v[16:31]
	s_waitcnt lgkmcnt(0)
	v_mfma_f32_32x32x16_bf16 v[32:47], v[4:7], v[108:111], v[32:47]
	ds_read_b128 v[0:3], v213
	ds_read_b128 v[4:7], v213 offset:4096
	s_waitcnt lgkmcnt(1)
	v_mfma_f32_32x32x16_bf16 v[16:31], v[0:3], v[104:107], v[16:31]
	ds_read_b128 v[0:3], v215
	s_waitcnt lgkmcnt(1)
	v_mfma_f32_32x32x16_bf16 v[32:47], v[4:7], v[104:107], v[32:47]
	ds_read_b128 v[4:7], v215 offset:4096
	v_cmp_gt_u32_e64 s[2:3], 32, v79
	s_waitcnt vmcnt(5) lgkmcnt(1)
	v_mfma_f32_32x32x16_bf16 v[16:31], v[0:3], v[100:103], v[16:31]
	v_add_co_u32_e32 v0, vcc, s70, v8
	v_and_b32_e32 v8, 0x3fffffc0, v51
	s_nop 0
	v_addc_co_u32_e32 v1, vcc, 0, v9, vcc
	ds_read_b128 v[0:3], v217
	s_waitcnt lgkmcnt(1)
	v_mfma_f32_32x32x16_bf16 v[32:47], v[4:7], v[100:103], v[32:47]
	v_and_b32_e32 v5, 0xc0, v75
	ds_read_b128 v[74:77], v217 offset:4096
	s_waitcnt vmcnt(0)
	s_waitcnt vmcnt(2)
	ds_write_b128 v198, v[62:65] offset:16384
	ds_write_b128 v199, v[54:57] offset:16384
	ds_write_b128 v200, v[58:61] offset:49152
	s_waitcnt vmcnt(1)
	ds_write_b128 v201, v[66:69] offset:49152
	s_waitcnt lgkmcnt(5)
	v_mfma_f32_32x32x16_bf16 v[16:31], v[0:3], v[96:99], v[16:31]
	v_mov_b32_e32 v54, 0xf149f2ca
	v_lshlrev_b32_e32 v4, 3, v79
	v_lshlrev_b32_e32 v6, 1, v49
	v_and_or_b32 v5, v4, 24, v5
	v_and_b32_e32 v0, 32, v6
	v_and_b32_e32 v1, 0x100, v4
	v_lshl_add_u32 v171, v8, 2, s65
	s_waitcnt lgkmcnt(4)
; #define SWAIT() do { if constexpr (SDEPTH == 2) asm volatile("s_waitcnt vmcnt(5)" ::: "memory"); else asm volatile("s_waitcnt vmcnt(0)" ::: "memory"); } while (0)
; __device__ __forceinline__ void partialSM(f32x16& p0, f32x16& p1, float& m_reg, float& mn, float& alpha) {
;   constexpr float C = SCALE * 1.4426950408889634f;
;   float pmax = p0[0];
; #pragma unroll
;   for (int r = 1; r < 16; ++r) pmax = fmaxf(pmax, p0[r]);
; #pragma unroll
;   for (int r = 0; r < 16; ++r) pmax = fmaxf(pmax, p1[r]);
;   { auto rr = __builtin_amdgcn_permlane32_swap(__float_as_uint(pmax), __float_as_uint(pmax), false, false);
;     pmax = fmaxf(__uint_as_float(rr[0]), __uint_as_float(rr[1])); }
;   if (__builtin_expect(__all(pmax - m_reg <= THR / SCALE), 1)) { mn = m_reg; alpha = 1.f; }
;   else { mn = fmaxf(m_reg, pmax); alpha = __builtin_amdgcn_exp2f((m_reg - mn) * C); m_reg = mn; }
;   float mnC = -mn * C;
; #pragma unroll
;   for (int r = 0; r < 16; ++r) p0[r] = fmaf(p0[r], C, mnC);
; #pragma unroll
;   for (int r = 0; r < 16; ++r) p1[r] = fmaf(p1[r], C, mnC);
; #pragma unroll
;   for (int r = 0; r < 16; ++r) p0[r] = __builtin_amdgcn_exp2f(p0[r]);
; }
; __device__ __forceinline__ void attn_dense_body(const bf16* __restrict__ Qb, const bf16* __restrict__ Kn, const bf16* __restrict__ Kr, const bf16* __restrict__ Vh,
;                                                 bf16* __restrict__ Ob, pg8::u64* ssa, int seq, char* lds, const int wv) {
;     ...
;   f32x16 pA0, pA1, pB0, pB1; float mnA, mnB, alA, alB; bf16x8 pa0, pa1, pa2, pa3; const int NT = seq / KVBLK;
;   constexpr int SE = 0, SO = SDEPTH - 1;
;   SLOAD(SE, 0); asm volatile("s_waitcnt vmcnt(0)" ::: "memory"); SWRITE(0, SE); __syncthreads();
;   qkt(pA0, pA1, K_lds, KR_lds, qr, ql, r32, hi); partialSM(pA0, pA1, m_reg, mnA, alA);
;   SLOAD(SO, KVBLK); if constexpr (SDEPTH == 2) { if (2 < NT) SLOAD(SE, 2 * KVBLK); }
;   SWAIT(); SWRITE(1, SO); __syncthreads();
	v_mfma_f32_32x32x16_bf16 v[32:47], v[74:77], v[96:99], v[32:47]
	s_nop 2
	v_max_f32_e32 v74, v17, v17
	v_max_f32_e32 v75, v16, v16
	v_max_f32_e32 v74, v75, v74
	v_max3_f32 v74, v74, v18, v19
	v_max3_f32 v74, v74, v20, v21
	v_max3_f32 v74, v74, v22, v23
	v_max3_f32 v74, v74, v24, v25
	v_max3_f32 v74, v74, v26, v27
	v_max3_f32 v74, v74, v28, v29
	v_max3_f32 v74, v74, v30, v31
	v_max3_f32 v74, v74, v32, v33
	v_max3_f32 v74, v74, v34, v35
	v_max3_f32 v74, v74, v36, v37
	v_max3_f32 v74, v74, v38, v39
	v_max3_f32 v74, v74, v40, v41
	v_max3_f32 v74, v74, v42, v43
	v_max3_f32 v74, v74, v44, v45
	v_max3_f32 v74, v74, v46, v47
	v_mov_b32_e32 v75, v74
	s_nop 1
	v_permlane32_swap_b32_e32 v74, v75
	v_max_f32_e32 v75, v75, v75
	v_max_f32_e32 v74, v74, v74
	v_max_f32_e32 v74, v74, v75
	v_add_f32_e32 v75, 0x7149f2ca, v74
	v_cmp_ge_f32_e32 vcc, s69, v75
	s_cmp_eq_u64 vcc, exec
	v_max_f32_e32 v55, 0xf149f2ca, v74
	s_cselect_b64 vcc, -1, 0
	v_cndmask_b32_e32 v223, v55, v54, vcc
	v_mul_f32_e32 v54, 0xbdd53b94, v223
	v_fmamk_f32 v16, v16, 0x3dd53b94, v54
	v_exp_f32_e32 v165, v16
	v_fmamk_f32 v16, v17, 0x3dd53b94, v54
	v_exp_f32_e32 v231, v16
	v_fmamk_f32 v16, v18, 0x3dd53b94, v54
	v_exp_f32_e32 v166, v16
	v_fmamk_f32 v16, v19, 0x3dd53b94, v54
	v_exp_f32_e32 v232, v16
	v_fmamk_f32 v16, v20, 0x3dd53b94, v54
	v_exp_f32_e32 v183, v16
	v_fmamk_f32 v16, v21, 0x3dd53b94, v54
	v_exp_f32_e32 v233, v16
	v_fmamk_f32 v16, v22, 0x3dd53b94, v54
	v_exp_f32_e32 v167, v16
	v_fmamk_f32 v16, v23, 0x3dd53b94, v54
	v_exp_f32_e32 v182, v16
	v_fmamk_f32 v16, v24, 0x3dd53b94, v54
	v_exp_f32_e32 v178, v16
	v_fmamk_f32 v16, v25, 0x3dd53b94, v54
	v_exp_f32_e32 v180, v16
	v_fmamk_f32 v16, v26, 0x3dd53b94, v54
	v_pk_fma_f32 v[148:149], v[38:39], s[52:53], v[54:55] op_sel_hi:[1,0,0]
	v_sub_f32_e32 v38, 0xf149f2ca, v55
	v_exp_f32_e32 v179, v16
	v_fmamk_f32 v16, v27, 0x3dd53b94, v54
	v_mul_f32_e32 v38, 0x3dd53b94, v38
	v_exp_f32_e32 v181, v16
	v_fmamk_f32 v16, v28, 0x3dd53b94, v54
	v_exp_f32_e32 v38, v38
	v_exp_f32_e32 v160, v16
	v_fmamk_f32 v16, v29, 0x3dd53b94, v54
	v_pk_fma_f32 v[146:147], v[46:47], s[52:53], v[54:55] op_sel_hi:[1,0,0]
	v_pk_fma_f32 v[150:151], v[44:45], s[52:53], v[54:55] op_sel_hi:[1,0,0]
	v_pk_fma_f32 v[154:155], v[42:43], s[52:53], v[54:55] op_sel_hi:[1,0,0]
	v_pk_fma_f32 v[144:145], v[40:41], s[52:53], v[54:55] op_sel_hi:[1,0,0]
	v_pk_fma_f32 v[152:153], v[36:37], s[52:53], v[54:55] op_sel_hi:[1,0,0]
	v_pk_fma_f32 v[156:157], v[34:35], s[52:53], v[54:55] op_sel_hi:[1,0,0]
	v_pk_fma_f32 v[158:159], v[32:33], s[52:53], v[54:55] op_sel_hi:[1,0,0]
	v_exp_f32_e32 v162, v16
	v_fmamk_f32 v16, v30, 0x3dd53b94, v54
	v_fmac_f32_e32 v54, 0x3dd53b94, v31
	v_or3_b32 v80, v5, v0, v1
	v_mov_b64_e32 v[0:1], s[36:37]
	v_exp_f32_e32 v161, v16
	v_exp_f32_e32 v163, v54
	v_mov_b32_e32 v49, v169
	v_mov_b32_e32 v51, v169
	v_mov_b64_e32 v[14:15], s[50:51]
	v_mov_b32_e32 v16, 0x1a00
	s_or_b32 s4, s4, s82
	v_add_u32_e32 v197, s62, v80
	v_mov_b64_e32 v[2:3], s[38:39]
	v_mov_b64_e32 v[4:5], s[40:41]
	v_mov_b64_e32 v[6:7], s[42:43]
	v_mov_b64_e32 v[8:9], s[44:45]
	v_mov_b64_e32 v[10:11], s[46:47]
	v_mov_b64_e32 v[12:13], s[48:49]
	v_cndmask_b32_e64 v220, v38, 1.0, vcc
	s_addk_i32 s62, 0x4000
	v_mad_u64_u32 v[172:173], s[60:61], s20, v16, v[52:53]
	v_lshl_add_u64 v[174:175], s[4:5], 0, v[50:51]
	v_lshl_add_u64 v[176:177], s[4:5], 0, v[48:49]
	v_mov_b64_e32 v[62:63], v[14:15]
	v_mov_b64_e32 v[46:47], v[14:15]
	v_mov_b64_e32 v[30:31], v[14:15]
	v_lshl_add_u32 v194, v193, 2, v171
	v_add_u32_e32 v196, s62, v80
	s_mov_b32 s20, 2
	v_mov_b64_e32 v[60:61], v[12:13]
	v_mov_b64_e32 v[58:59], v[10:11]
	v_mov_b64_e32 v[56:57], v[8:9]
	v_mov_b64_e32 v[54:55], v[6:7]
	v_mov_b64_e32 v[52:53], v[4:5]
	v_mov_b64_e32 v[50:51], v[2:3]
	v_mov_b64_e32 v[48:49], v[0:1]
	v_mov_b64_e32 v[44:45], v[12:13]
	v_mov_b64_e32 v[42:43], v[10:11]
	v_mov_b64_e32 v[40:41], v[8:9]
	v_mov_b64_e32 v[38:39], v[6:7]
	v_mov_b64_e32 v[36:37], v[4:5]
	v_mov_b64_e32 v[34:35], v[2:3]
	v_mov_b64_e32 v[32:33], v[0:1]
	v_mov_b64_e32 v[28:29], v[12:13]
	v_mov_b64_e32 v[26:27], v[10:11]
	v_mov_b64_e32 v[24:25], v[8:9]
	v_mov_b64_e32 v[22:23], v[6:7]
	v_mov_b64_e32 v[20:21], v[4:5]
	v_mov_b64_e32 v[18:19], v[2:3]
	v_mov_b64_e32 v[16:17], v[0:1]
	s_waitcnt vmcnt(0)
	ds_write_b128 v219, v[70:73]
	s_waitcnt lgkmcnt(0)
	s_barrier
